# speedup vs baseline: 1.0258x; 1.0110x over previous
.LBB0_98:
	s_mul_i32 s87, s87, 7
	s_sub_i32 s0, s24, s87
	s_mul_i32 s16, s0, 9
	s_add_i32 s1, s16, 9
	s_cmp_lg_u32 s0, 6
	s_cselect_b32 s17, s1, 64
	s_cmp_ge_i32 s16, s17
	s_waitcnt lgkmcnt(0)
	s_barrier
	s_cbranch_scc1 .LBB0_64
	s_and_b64 s[0:1], s[2:3], exec
	v_readlane_b32 s0, v254, 60
	v_readlane_b32 s1, v254, 61
	v_readlane_b32 s6, v255, 0
	s_cselect_b32 s1, s1, s6
	v_readlane_b32 s6, v254, 62
	s_cselect_b32 s0, s0, s6
	s_lshl_b32 s8, s86, 6
	s_and_b64 s[2:3], s[2:3], exec
	v_or_b32_e32 v29, s8, v3
	s_cselect_b32 s28, 12, 9
	s_lshl_b32 s2, s82, 1
	v_sub_u32_e32 v8, s2, v29
	v_mov_b32_e32 v9, s82
	v_cmp_eq_u32_e64 s[6:7], 0, v29
	s_mov_b32 s29, s28
	v_add_u32_e32 v31, s8, v23
	v_cndmask_b32_e64 v30, v8, v9, s[6:7]
	v_lshrrev_b32_e32 v56, 6, v180
	v_and_b32_e32 v56, 1, v56
	v_and_b32_e32 v58, 31, v180
	v_lshl_or_b32 v58, v56, 5, v58
	v_bfe_u32 v59, v180, 5, 1
	v_lshlrev_b32_e32 v58, 8, v58
	v_lshl_add_u32 v58, v59, 7, v58
	ds_read_b128 v[52:55], v58 offset:25600
	ds_read_b128 v[60:63], v58 offset:25616
	ds_read_b128 v[64:67], v58 offset:25632
	ds_read_b128 v[68:71], v58 offset:25648
	ds_read_b128 v[80:83], v58 offset:25664
	ds_read_b128 v[84:87], v58 offset:25680
	ds_read_b128 v[88:91], v58 offset:25696
	ds_read_b128 v[92:95], v58 offset:25712
.LBB0_100:
	s_lshl_b32 s2, s16, 7
	s_and_b32 s30, s2, 0x780
	v_readlane_b32 s52, v254, 43
	v_readlane_b32 s64, v254, 55
	v_readlane_b32 s65, v254, 56
	v_readlane_b32 s53, v254, 44
	v_readlane_b32 s54, v254, 45
	v_readlane_b32 s55, v254, 46
	v_readlane_b32 s56, v254, 47
	v_readlane_b32 s57, v254, 48
	v_readlane_b32 s58, v254, 49
	v_readlane_b32 s59, v254, 50
	v_readlane_b32 s60, v254, 51
	v_readlane_b32 s61, v254, 52
	v_readlane_b32 s62, v254, 53
	v_readlane_b32 s63, v254, 54
	v_readlane_b32 s66, v254, 57
	v_readlane_b32 s67, v254, 58
	v_lshrrev_b32_e32 v56, 6, v180
	v_and_b32_e32 v58, 31, v180
	v_lshrrev_b32_e32 v59, 1, v56
	v_lshl_or_b32 v58, v59, 5, v58
	v_bfe_u32 v59, v180, 5, 1
	v_and_b32_e32 v56, 1, v56
	v_lshlrev_b32_e32 v79, 2, v58
	v_lshl_add_u32 v79, v59, 20, v79
	s_lshl_b32 s3, s16, 9
	s_add_u32 s2, s64, s3
	s_addc_u32 s3, s65, 0
	s_mov_b32 s34, 0x3fb8aa3b
	global_load_dword v8, v79, s[2:3]
	s_add_u32 s2, s2, 0x8000
	s_addc_u32 s3, s3, 0
	global_load_dword v9, v79, s[2:3]
	s_add_u32 s2, s2, 0x8000
	s_addc_u32 s3, s3, 0
	global_load_dword v10, v79, s[2:3]
	s_add_u32 s2, s2, 0x8000
	s_addc_u32 s3, s3, 0
	global_load_dword v11, v79, s[2:3]
	s_add_u32 s2, s2, 0x8000
	s_addc_u32 s3, s3, 0
	global_load_dword v12, v79, s[2:3]
	s_add_u32 s2, s2, 0x8000
	s_addc_u32 s3, s3, 0
	global_load_dword v13, v79, s[2:3]
	s_add_u32 s2, s2, 0x8000
	s_addc_u32 s3, s3, 0
	global_load_dword v14, v79, s[2:3]
	s_add_u32 s2, s2, 0x8000
	s_addc_u32 s3, s3, 0
	global_load_dword v15, v79, s[2:3]
	s_add_u32 s2, s2, 0x8000
	s_addc_u32 s3, s3, 0
	global_load_dword v16, v79, s[2:3]
	s_add_u32 s2, s2, 0x8000
	s_addc_u32 s3, s3, 0
	global_load_dword v17, v79, s[2:3]
	s_add_u32 s2, s2, 0x8000
	s_addc_u32 s3, s3, 0
	global_load_dword v18, v79, s[2:3]
	s_add_u32 s2, s2, 0x8000
	s_addc_u32 s3, s3, 0
	global_load_dword v19, v79, s[2:3]
	s_add_u32 s2, s2, 0x8000
	s_addc_u32 s3, s3, 0
	global_load_dword v32, v79, s[2:3]
	s_add_u32 s2, s2, 0x8000
	s_addc_u32 s3, s3, 0
	global_load_dword v33, v79, s[2:3]
	s_add_u32 s2, s2, 0x8000
	s_addc_u32 s3, s3, 0
	global_load_dword v34, v79, s[2:3]
	s_add_u32 s2, s2, 0x8000
	s_addc_u32 s3, s3, 0
	global_load_dword v35, v79, s[2:3]
	s_add_u32 s2, s2, 0x8000
	s_addc_u32 s3, s3, 0
	global_load_dword v36, v79, s[2:3]
	s_add_u32 s2, s2, 0x8000
	s_addc_u32 s3, s3, 0
	global_load_dword v37, v79, s[2:3]
	s_add_u32 s2, s2, 0x8000
	s_addc_u32 s3, s3, 0
	global_load_dword v38, v79, s[2:3]
	s_add_u32 s2, s2, 0x8000
	s_addc_u32 s3, s3, 0
	global_load_dword v39, v79, s[2:3]
	s_add_u32 s2, s2, 0x8000
	s_addc_u32 s3, s3, 0
	global_load_dword v40, v79, s[2:3]
	s_add_u32 s2, s2, 0x8000
	s_addc_u32 s3, s3, 0
	global_load_dword v41, v79, s[2:3]
	s_add_u32 s2, s2, 0x8000
	s_addc_u32 s3, s3, 0
	global_load_dword v42, v79, s[2:3]
	s_add_u32 s2, s2, 0x8000
	s_addc_u32 s3, s3, 0
	global_load_dword v43, v79, s[2:3]
	s_add_u32 s2, s2, 0x8000
	s_addc_u32 s3, s3, 0
	global_load_dword v44, v79, s[2:3]
	s_add_u32 s2, s2, 0x8000
	s_addc_u32 s3, s3, 0
	global_load_dword v45, v79, s[2:3]
	s_add_u32 s2, s2, 0x8000
	s_addc_u32 s3, s3, 0
	global_load_dword v46, v79, s[2:3]
	s_add_u32 s2, s2, 0x8000
	s_addc_u32 s3, s3, 0
	global_load_dword v47, v79, s[2:3]
	s_add_u32 s2, s2, 0x8000
	s_addc_u32 s3, s3, 0
	global_load_dword v48, v79, s[2:3]
	s_add_u32 s2, s2, 0x8000
	s_addc_u32 s3, s3, 0
	global_load_dword v49, v79, s[2:3]
	s_add_u32 s2, s2, 0x8000
	s_addc_u32 s3, s3, 0
	global_load_dword v50, v79, s[2:3]
	s_add_u32 s2, s2, 0x8000
	s_addc_u32 s3, s3, 0
	global_load_dword v51, v79, s[2:3]
	s_waitcnt lgkmcnt(0)
	s_waitcnt vmcnt(31)
	v_mfma_f32_32x32x2_f32 v[96:111], v52, v8, 0
	s_waitcnt vmcnt(30)
	v_mfma_f32_32x32x2_f32 v[96:111], v53, v9, v[96:111]
	s_waitcnt vmcnt(29)
	v_mfma_f32_32x32x2_f32 v[96:111], v54, v10, v[96:111]
	s_waitcnt vmcnt(28)
	v_mfma_f32_32x32x2_f32 v[96:111], v55, v11, v[96:111]
	s_waitcnt vmcnt(27)
	v_mfma_f32_32x32x2_f32 v[96:111], v60, v12, v[96:111]
	s_waitcnt vmcnt(26)
	v_mfma_f32_32x32x2_f32 v[96:111], v61, v13, v[96:111]
	s_waitcnt vmcnt(25)
	v_mfma_f32_32x32x2_f32 v[96:111], v62, v14, v[96:111]
	s_waitcnt vmcnt(24)
	v_mfma_f32_32x32x2_f32 v[96:111], v63, v15, v[96:111]
	s_waitcnt vmcnt(23)
	v_mfma_f32_32x32x2_f32 v[96:111], v64, v16, v[96:111]
	s_waitcnt vmcnt(22)
	v_mfma_f32_32x32x2_f32 v[96:111], v65, v17, v[96:111]
	s_waitcnt vmcnt(21)
	v_mfma_f32_32x32x2_f32 v[96:111], v66, v18, v[96:111]
	s_waitcnt vmcnt(20)
	v_mfma_f32_32x32x2_f32 v[96:111], v67, v19, v[96:111]
	s_waitcnt vmcnt(19)
	v_mfma_f32_32x32x2_f32 v[96:111], v68, v32, v[96:111]
	s_waitcnt vmcnt(18)
	v_mfma_f32_32x32x2_f32 v[96:111], v69, v33, v[96:111]
	s_waitcnt vmcnt(17)
	v_mfma_f32_32x32x2_f32 v[96:111], v70, v34, v[96:111]
	s_waitcnt vmcnt(16)
	v_mfma_f32_32x32x2_f32 v[96:111], v71, v35, v[96:111]
	s_waitcnt vmcnt(15)
	v_mfma_f32_32x32x2_f32 v[96:111], v80, v36, v[96:111]
	s_waitcnt vmcnt(14)
	v_mfma_f32_32x32x2_f32 v[96:111], v81, v37, v[96:111]
	s_waitcnt vmcnt(13)
	v_mfma_f32_32x32x2_f32 v[96:111], v82, v38, v[96:111]
	s_waitcnt vmcnt(12)
	v_mfma_f32_32x32x2_f32 v[96:111], v83, v39, v[96:111]
	s_waitcnt vmcnt(11)
	v_mfma_f32_32x32x2_f32 v[96:111], v84, v40, v[96:111]
	s_waitcnt vmcnt(10)
	v_mfma_f32_32x32x2_f32 v[96:111], v85, v41, v[96:111]
	s_waitcnt vmcnt(9)
	v_mfma_f32_32x32x2_f32 v[96:111], v86, v42, v[96:111]
	s_waitcnt vmcnt(8)
	v_mfma_f32_32x32x2_f32 v[96:111], v87, v43, v[96:111]
	s_waitcnt vmcnt(7)
	v_mfma_f32_32x32x2_f32 v[96:111], v88, v44, v[96:111]
	s_waitcnt vmcnt(6)
	v_mfma_f32_32x32x2_f32 v[96:111], v89, v45, v[96:111]
	s_waitcnt vmcnt(5)
	v_mfma_f32_32x32x2_f32 v[96:111], v90, v46, v[96:111]
	s_waitcnt vmcnt(4)
	v_mfma_f32_32x32x2_f32 v[96:111], v91, v47, v[96:111]
	s_waitcnt vmcnt(3)
	v_mfma_f32_32x32x2_f32 v[96:111], v92, v48, v[96:111]
	s_waitcnt vmcnt(2)
	v_mfma_f32_32x32x2_f32 v[96:111], v93, v49, v[96:111]
	s_waitcnt vmcnt(1)
	v_mfma_f32_32x32x2_f32 v[96:111], v94, v50, v[96:111]
	s_waitcnt vmcnt(0)
	v_mfma_f32_32x32x2_f32 v[96:111], v95, v51, v[96:111]
	s_nop 7
	v_or_b32_e32 v8, s30, v58
	v_cvt_f32_u32_e32 v9, v8
	v_div_scale_f32 v10, s[2:3], s84, s84, v9
	v_rcp_f32_e32 v11, v10
	v_div_scale_f32 v12, vcc, v9, s84, v9
	v_fma_f32 v13, -v10, v11, 1.0
	v_fmac_f32_e32 v11, v13, v11
	v_mul_f32_e32 v13, v12, v11
	v_fma_f32 v14, -v10, v13, v12
	v_fmac_f32_e32 v13, v14, v11
	v_fma_f32 v10, -v10, v13, v12
	v_div_fmas_f32 v15, v10, v11, v13
	v_div_fixup_f32 v16, v15, s84, v9
	v_fmamk_f32 v16, v16, 0x41447cbd, v74
	v_sub_u32_e32 v17, v31, v23
	v_lshl_add_u32 v17, v56, 5, v17
	v_lshl_add_u32 v17, v59, 2, v17
	v_mul_u32_u24_e32 v18, 0x104, v58
	v_lshl_add_u32 v18, v56, 7, v18
	v_lshl_add_u32 v18, v59, 4, v18
	s_nop 1
	v_add_u32_e32 v32, 0, v17
	v_cvt_f32_i32_e32 v32, v32
	v_mul_f32_e64 v32, v28, -v32
	v_mul_f32_e32 v32, v16, v32
	v_mul_f32_e32 v33, 0x3fb8aa3b, v32
	v_fma_f32 v34, v32, s34, -v33
	v_rndne_f32_e32 v35, v33
	v_fmac_f32_e32 v34, 0x32a5705f, v32
	v_sub_f32_e32 v33, v33, v35
	v_add_f32_e32 v33, v33, v34
	v_exp_f32_e32 v33, v33
	v_cvt_i32_f32_e32 v34, v35
	v_cmp_ngt_f32_e32 vcc, 0xc2ce8ed0, v32
	s_nop 0
	v_ldexp_f32 v33, v33, v34
	v_cndmask_b32_e32 v33, 0, v33, vcc
	v_cmp_nlt_f32_e32 vcc, 0x42b17218, v32
	s_nop 1
	v_cndmask_b32_e32 v32, v78, v33, vcc
	v_mul_f32_e32 v32, v32, v96
	ds_write_b32 v18, v32 offset:41984
	v_add_u32_e32 v36, 1, v17
	v_cvt_f32_i32_e32 v36, v36
	v_mul_f32_e64 v36, v28, -v36
	v_mul_f32_e32 v36, v16, v36
	v_mul_f32_e32 v37, 0x3fb8aa3b, v36
	v_fma_f32 v38, v36, s34, -v37
	v_rndne_f32_e32 v39, v37
	v_fmac_f32_e32 v38, 0x32a5705f, v36
	v_sub_f32_e32 v37, v37, v39
	v_add_f32_e32 v37, v37, v38
	v_exp_f32_e32 v37, v37
	v_cvt_i32_f32_e32 v38, v39
	v_cmp_ngt_f32_e32 vcc, 0xc2ce8ed0, v36
	s_nop 0
	v_ldexp_f32 v37, v37, v38
	v_cndmask_b32_e32 v37, 0, v37, vcc
	v_cmp_nlt_f32_e32 vcc, 0x42b17218, v36
	s_nop 1
	v_cndmask_b32_e32 v36, v78, v37, vcc
	v_mul_f32_e32 v36, v36, v97
	ds_write_b32 v18, v36 offset:41988
	v_add_u32_e32 v32, 2, v17
	v_cvt_f32_i32_e32 v32, v32
	v_mul_f32_e64 v32, v28, -v32
	v_mul_f32_e32 v32, v16, v32
	v_mul_f32_e32 v33, 0x3fb8aa3b, v32
	v_fma_f32 v34, v32, s34, -v33
	v_rndne_f32_e32 v35, v33
	v_fmac_f32_e32 v34, 0x32a5705f, v32
	v_sub_f32_e32 v33, v33, v35
	v_add_f32_e32 v33, v33, v34
	v_exp_f32_e32 v33, v33
	v_cvt_i32_f32_e32 v34, v35
	v_cmp_ngt_f32_e32 vcc, 0xc2ce8ed0, v32
	s_nop 0
	v_ldexp_f32 v33, v33, v34
	v_cndmask_b32_e32 v33, 0, v33, vcc
	v_cmp_nlt_f32_e32 vcc, 0x42b17218, v32
	s_nop 1
	v_cndmask_b32_e32 v32, v78, v33, vcc
	v_mul_f32_e32 v32, v32, v98
	ds_write_b32 v18, v32 offset:41992
	v_add_u32_e32 v36, 3, v17
	v_cvt_f32_i32_e32 v36, v36
	v_mul_f32_e64 v36, v28, -v36
	v_mul_f32_e32 v36, v16, v36
	v_mul_f32_e32 v37, 0x3fb8aa3b, v36
	v_fma_f32 v38, v36, s34, -v37
	v_rndne_f32_e32 v39, v37
	v_fmac_f32_e32 v38, 0x32a5705f, v36
	v_sub_f32_e32 v37, v37, v39
	v_add_f32_e32 v37, v37, v38
	v_exp_f32_e32 v37, v37
	v_cvt_i32_f32_e32 v38, v39
	v_cmp_ngt_f32_e32 vcc, 0xc2ce8ed0, v36
	s_nop 0
	v_ldexp_f32 v37, v37, v38
	v_cndmask_b32_e32 v37, 0, v37, vcc
	v_cmp_nlt_f32_e32 vcc, 0x42b17218, v36
	s_nop 1
	v_cndmask_b32_e32 v36, v78, v37, vcc
	v_mul_f32_e32 v36, v36, v99
	ds_write_b32 v18, v36 offset:41996
	v_add_u32_e32 v32, 8, v17
	v_cvt_f32_i32_e32 v32, v32
	v_mul_f32_e64 v32, v28, -v32
	v_mul_f32_e32 v32, v16, v32
	v_mul_f32_e32 v33, 0x3fb8aa3b, v32
	v_fma_f32 v34, v32, s34, -v33
	v_rndne_f32_e32 v35, v33
	v_fmac_f32_e32 v34, 0x32a5705f, v32
	v_sub_f32_e32 v33, v33, v35
	v_add_f32_e32 v33, v33, v34
	v_exp_f32_e32 v33, v33
	v_cvt_i32_f32_e32 v34, v35
	v_cmp_ngt_f32_e32 vcc, 0xc2ce8ed0, v32
	s_nop 0
	v_ldexp_f32 v33, v33, v34
	v_cndmask_b32_e32 v33, 0, v33, vcc
	v_cmp_nlt_f32_e32 vcc, 0x42b17218, v32
	s_nop 1
	v_cndmask_b32_e32 v32, v78, v33, vcc
	v_mul_f32_e32 v32, v32, v100
	ds_write_b32 v18, v32 offset:42016
	v_add_u32_e32 v36, 9, v17
	v_cvt_f32_i32_e32 v36, v36
	v_mul_f32_e64 v36, v28, -v36
	v_mul_f32_e32 v36, v16, v36
	v_mul_f32_e32 v37, 0x3fb8aa3b, v36
	v_fma_f32 v38, v36, s34, -v37
	v_rndne_f32_e32 v39, v37
	v_fmac_f32_e32 v38, 0x32a5705f, v36
	v_sub_f32_e32 v37, v37, v39
	v_add_f32_e32 v37, v37, v38
	v_exp_f32_e32 v37, v37
	v_cvt_i32_f32_e32 v38, v39
	v_cmp_ngt_f32_e32 vcc, 0xc2ce8ed0, v36
	s_nop 0
	v_ldexp_f32 v37, v37, v38
	v_cndmask_b32_e32 v37, 0, v37, vcc
	v_cmp_nlt_f32_e32 vcc, 0x42b17218, v36
	s_nop 1
	v_cndmask_b32_e32 v36, v78, v37, vcc
	v_mul_f32_e32 v36, v36, v101
	ds_write_b32 v18, v36 offset:42020
	v_add_u32_e32 v32, 10, v17
	v_cvt_f32_i32_e32 v32, v32
	v_mul_f32_e64 v32, v28, -v32
	v_mul_f32_e32 v32, v16, v32
	v_mul_f32_e32 v33, 0x3fb8aa3b, v32
	v_fma_f32 v34, v32, s34, -v33
	v_rndne_f32_e32 v35, v33
	v_fmac_f32_e32 v34, 0x32a5705f, v32
	v_sub_f32_e32 v33, v33, v35
	v_add_f32_e32 v33, v33, v34
	v_exp_f32_e32 v33, v33
	v_cvt_i32_f32_e32 v34, v35
	v_cmp_ngt_f32_e32 vcc, 0xc2ce8ed0, v32
	s_nop 0
	v_ldexp_f32 v33, v33, v34
	v_cndmask_b32_e32 v33, 0, v33, vcc
	v_cmp_nlt_f32_e32 vcc, 0x42b17218, v32
	s_nop 1
	v_cndmask_b32_e32 v32, v78, v33, vcc
	v_mul_f32_e32 v32, v32, v102
	ds_write_b32 v18, v32 offset:42024
	v_add_u32_e32 v36, 11, v17
	v_cvt_f32_i32_e32 v36, v36
	v_mul_f32_e64 v36, v28, -v36
	v_mul_f32_e32 v36, v16, v36
	v_mul_f32_e32 v37, 0x3fb8aa3b, v36
	v_fma_f32 v38, v36, s34, -v37
	v_rndne_f32_e32 v39, v37
	v_fmac_f32_e32 v38, 0x32a5705f, v36
	v_sub_f32_e32 v37, v37, v39
	v_add_f32_e32 v37, v37, v38
	v_exp_f32_e32 v37, v37
	v_cvt_i32_f32_e32 v38, v39
	v_cmp_ngt_f32_e32 vcc, 0xc2ce8ed0, v36
	s_nop 0
	v_ldexp_f32 v37, v37, v38
	v_cndmask_b32_e32 v37, 0, v37, vcc
	v_cmp_nlt_f32_e32 vcc, 0x42b17218, v36
	s_nop 1
	v_cndmask_b32_e32 v36, v78, v37, vcc
	v_mul_f32_e32 v36, v36, v103
	ds_write_b32 v18, v36 offset:42028
	v_add_u32_e32 v32, 16, v17
	v_cvt_f32_i32_e32 v32, v32
	v_mul_f32_e64 v32, v28, -v32
	v_mul_f32_e32 v32, v16, v32
	v_mul_f32_e32 v33, 0x3fb8aa3b, v32
	v_fma_f32 v34, v32, s34, -v33
	v_rndne_f32_e32 v35, v33
	v_fmac_f32_e32 v34, 0x32a5705f, v32
	v_sub_f32_e32 v33, v33, v35
	v_add_f32_e32 v33, v33, v34
	v_exp_f32_e32 v33, v33
	v_cvt_i32_f32_e32 v34, v35
	v_cmp_ngt_f32_e32 vcc, 0xc2ce8ed0, v32
	s_nop 0
	v_ldexp_f32 v33, v33, v34
	v_cndmask_b32_e32 v33, 0, v33, vcc
	v_cmp_nlt_f32_e32 vcc, 0x42b17218, v32
	s_nop 1
	v_cndmask_b32_e32 v32, v78, v33, vcc
	v_mul_f32_e32 v32, v32, v104
	ds_write_b32 v18, v32 offset:42048
	v_add_u32_e32 v36, 17, v17
	v_cvt_f32_i32_e32 v36, v36
	v_mul_f32_e64 v36, v28, -v36
	v_mul_f32_e32 v36, v16, v36
	v_mul_f32_e32 v37, 0x3fb8aa3b, v36
	v_fma_f32 v38, v36, s34, -v37
	v_rndne_f32_e32 v39, v37
	v_fmac_f32_e32 v38, 0x32a5705f, v36
	v_sub_f32_e32 v37, v37, v39
	v_add_f32_e32 v37, v37, v38
	v_exp_f32_e32 v37, v37
	v_cvt_i32_f32_e32 v38, v39
	v_cmp_ngt_f32_e32 vcc, 0xc2ce8ed0, v36
	s_nop 0
	v_ldexp_f32 v37, v37, v38
	v_cndmask_b32_e32 v37, 0, v37, vcc
	v_cmp_nlt_f32_e32 vcc, 0x42b17218, v36
	s_nop 1
	v_cndmask_b32_e32 v36, v78, v37, vcc
	v_mul_f32_e32 v36, v36, v105
	ds_write_b32 v18, v36 offset:42052
	v_add_u32_e32 v32, 18, v17
	v_cvt_f32_i32_e32 v32, v32
	v_mul_f32_e64 v32, v28, -v32
	v_mul_f32_e32 v32, v16, v32
	v_mul_f32_e32 v33, 0x3fb8aa3b, v32
	v_fma_f32 v34, v32, s34, -v33
	v_rndne_f32_e32 v35, v33
	v_fmac_f32_e32 v34, 0x32a5705f, v32
	v_sub_f32_e32 v33, v33, v35
	v_add_f32_e32 v33, v33, v34
	v_exp_f32_e32 v33, v33
	v_cvt_i32_f32_e32 v34, v35
	v_cmp_ngt_f32_e32 vcc, 0xc2ce8ed0, v32
	s_nop 0
	v_ldexp_f32 v33, v33, v34
	v_cndmask_b32_e32 v33, 0, v33, vcc
	v_cmp_nlt_f32_e32 vcc, 0x42b17218, v32
	s_nop 1
	v_cndmask_b32_e32 v32, v78, v33, vcc
	v_mul_f32_e32 v32, v32, v106
	ds_write_b32 v18, v32 offset:42056
	v_add_u32_e32 v36, 19, v17
	v_cvt_f32_i32_e32 v36, v36
	v_mul_f32_e64 v36, v28, -v36
	v_mul_f32_e32 v36, v16, v36
	v_mul_f32_e32 v37, 0x3fb8aa3b, v36
	v_fma_f32 v38, v36, s34, -v37
	v_rndne_f32_e32 v39, v37
	v_fmac_f32_e32 v38, 0x32a5705f, v36
	v_sub_f32_e32 v37, v37, v39
	v_add_f32_e32 v37, v37, v38
	v_exp_f32_e32 v37, v37
	v_cvt_i32_f32_e32 v38, v39
	v_cmp_ngt_f32_e32 vcc, 0xc2ce8ed0, v36
	s_nop 0
	v_ldexp_f32 v37, v37, v38
	v_cndmask_b32_e32 v37, 0, v37, vcc
	v_cmp_nlt_f32_e32 vcc, 0x42b17218, v36
	s_nop 1
	v_cndmask_b32_e32 v36, v78, v37, vcc
	v_mul_f32_e32 v36, v36, v107
	ds_write_b32 v18, v36 offset:42060
	v_add_u32_e32 v32, 24, v17
	v_cvt_f32_i32_e32 v32, v32
	v_mul_f32_e64 v32, v28, -v32
	v_mul_f32_e32 v32, v16, v32
	v_mul_f32_e32 v33, 0x3fb8aa3b, v32
	v_fma_f32 v34, v32, s34, -v33
	v_rndne_f32_e32 v35, v33
	v_fmac_f32_e32 v34, 0x32a5705f, v32
	v_sub_f32_e32 v33, v33, v35
	v_add_f32_e32 v33, v33, v34
	v_exp_f32_e32 v33, v33
	v_cvt_i32_f32_e32 v34, v35
	v_cmp_ngt_f32_e32 vcc, 0xc2ce8ed0, v32
	s_nop 0
	v_ldexp_f32 v33, v33, v34
	v_cndmask_b32_e32 v33, 0, v33, vcc
	v_cmp_nlt_f32_e32 vcc, 0x42b17218, v32
	s_nop 1
	v_cndmask_b32_e32 v32, v78, v33, vcc
	v_mul_f32_e32 v32, v32, v108
	ds_write_b32 v18, v32 offset:42080
	v_add_u32_e32 v36, 25, v17
	v_cvt_f32_i32_e32 v36, v36
	v_mul_f32_e64 v36, v28, -v36
	v_mul_f32_e32 v36, v16, v36
	v_mul_f32_e32 v37, 0x3fb8aa3b, v36
	v_fma_f32 v38, v36, s34, -v37
	v_rndne_f32_e32 v39, v37
	v_fmac_f32_e32 v38, 0x32a5705f, v36
	v_sub_f32_e32 v37, v37, v39
	v_add_f32_e32 v37, v37, v38
	v_exp_f32_e32 v37, v37
	v_cvt_i32_f32_e32 v38, v39
	v_cmp_ngt_f32_e32 vcc, 0xc2ce8ed0, v36
	s_nop 0
	v_ldexp_f32 v37, v37, v38
	v_cndmask_b32_e32 v37, 0, v37, vcc
	v_cmp_nlt_f32_e32 vcc, 0x42b17218, v36
	s_nop 1
	v_cndmask_b32_e32 v36, v78, v37, vcc
	v_mul_f32_e32 v36, v36, v109
	ds_write_b32 v18, v36 offset:42084
	v_add_u32_e32 v32, 26, v17
	v_cvt_f32_i32_e32 v32, v32
	v_mul_f32_e64 v32, v28, -v32
	v_mul_f32_e32 v32, v16, v32
	v_mul_f32_e32 v33, 0x3fb8aa3b, v32
	v_fma_f32 v34, v32, s34, -v33
	v_rndne_f32_e32 v35, v33
	v_fmac_f32_e32 v34, 0x32a5705f, v32
	v_sub_f32_e32 v33, v33, v35
	v_add_f32_e32 v33, v33, v34
	v_exp_f32_e32 v33, v33
	v_cvt_i32_f32_e32 v34, v35
	v_cmp_ngt_f32_e32 vcc, 0xc2ce8ed0, v32
	s_nop 0
	v_ldexp_f32 v33, v33, v34
	v_cndmask_b32_e32 v33, 0, v33, vcc
	v_cmp_nlt_f32_e32 vcc, 0x42b17218, v32
	s_nop 1
	v_cndmask_b32_e32 v32, v78, v33, vcc
	v_mul_f32_e32 v32, v32, v110
	ds_write_b32 v18, v32 offset:42088
	v_add_u32_e32 v36, 27, v17
	v_cvt_f32_i32_e32 v36, v36
	v_mul_f32_e64 v36, v28, -v36
	v_mul_f32_e32 v36, v16, v36
	v_mul_f32_e32 v37, 0x3fb8aa3b, v36
	v_fma_f32 v38, v36, s34, -v37
	v_rndne_f32_e32 v39, v37
	v_fmac_f32_e32 v38, 0x32a5705f, v36
	v_sub_f32_e32 v37, v37, v39
	v_add_f32_e32 v37, v37, v38
	v_exp_f32_e32 v37, v37
	v_cvt_i32_f32_e32 v38, v39
	v_cmp_ngt_f32_e32 vcc, 0xc2ce8ed0, v36
	s_nop 0
	v_ldexp_f32 v37, v37, v38
	v_cndmask_b32_e32 v37, 0, v37, vcc
	v_cmp_nlt_f32_e32 vcc, 0x42b17218, v36
	s_nop 1
	v_cndmask_b32_e32 v36, v78, v37, vcc
	v_mul_f32_e32 v36, v36, v111
	ds_write_b32 v18, v36 offset:42092
	s_bitcmp0_b32 s16, 4
	s_cselect_b64 vcc, -1, 0
	s_ashr_i32 s2, s16, 5
	v_cndmask_b32_e32 v8, v30, v29, vcc
	s_ashr_i32 s3, s2, 31
	v_ashrrev_i32_e32 v9, 31, v8
	s_lshl_b64 s[2:3], s[2:3], 11
	s_mov_b32 s31, 16
	s_mov_b32 s34, 0
	v_lshl_add_u64 v[8:9], v[8:9], 2, s[0:1]
	s_mov_b32 s8, s2
	s_mov_b32 s9, s3
	s_mov_b32 s35, s30
	s_mov_b32 s36, 1
	s_waitcnt lgkmcnt(0)
	s_barrier
